# filter-tap tiles rebalanced: 1024 (was 1280) computed by the workgroups that have one projection unit fewer, the rest in the next phase; on this chip 10 tap tiles took longer than one GEMM unit
# speedup vs baseline: 1.0063x; 1.0063x over previous
.LBB0_502:
	s_mov_b64 s[2:3], s[96:97]
	s_mov_b32 s4, s93
	s_mov_b32 s5, s94
	s_cmpk_eq_i32 s5, 0x100
	s_cselect_b64 s[6:7], -1, 0
	s_cmpk_gt_i32 s4, 0x7f
	s_cselect_b64 s[8:9], -1, 0
	s_and_b64 s[6:7], s[8:9], s[6:7]
	s_cmpk_lt_u32 s4, 0x480
	s_cselect_b64 s[8:9], -1, 0
	s_and_b64 s[6:7], s[6:7], s[8:9]
	v_mov_b32_e32 v0, v192
	s_and_b64 vcc, exec, s[6:7]
	s_cbranch_vccz .LBB0_511
	s_load_dwordx2 s[6:7], s[2:3], 0x50
	s_load_dwordx4 s[40:43], s[2:3], 0xc0
	v_readlane_b32 s8, v255, 20
	v_readlane_b32 s9, v255, 21
	s_mov_b32 s9, s75
	s_lshl_b64 s[2:3], s[8:9], 19
	s_waitcnt lgkmcnt(0)
	s_add_u32 s2, s6, s2
	s_mov_b32 s6, s8
	s_addc_u32 s3, s7, s3
	v_writelane_b32 v255, s6, 20
	v_lshlrev_b32_e32 v1, 2, v0
	v_and_b32_e32 v4, 60, v1
	v_writelane_b32 v255, s7, 21
	s_lshl_b64 s[6:7], s[8:9], 21
	s_add_u32 s6, s42, s6
	s_addc_u32 s7, s43, s7
	v_lshlrev_b32_e32 v194, 2, v4
	v_and_b32_e32 v21, 0x7c, v1
	v_lshlrev_b32_e32 v1, 4, v0
	v_lshl_add_u64 v[2:3], s[6:7], 0, v[194:195]
	s_mov_b64 s[6:7], 0x22200000
	v_lshl_add_u64 v[18:19], s[2:3], 0, v[194:195]
	s_movk_i32 s2, 0x210
	v_ashrrev_i32_e32 v34, 3, v0
	v_and_b32_e32 v20, 0x70, v1
	v_lshl_add_u64 v[16:17], v[2:3], 0, s[6:7]
	v_mad_u32_u24 v2, v4, s2, 0
	v_mul_i32_i24_e32 v3, 0xfffffdf4, v4
	v_mul_lo_u32 v4, v34, s2
	v_lshlrev_b32_e32 v5, 2, v20
	v_add3_u32 v37, 0, v4, v5
	v_add_u32_e32 v4, 0x200, v0
	v_ashrrev_i32_e32 v22, 4, v0
	v_ashrrev_i32_e32 v24, 4, v4
	v_add_u32_e32 v4, 0x400, v0
	v_add_u32_e32 v0, 0x600, v0
	v_ashrrev_i32_e32 v38, 4, v4
	v_ashrrev_i32_e32 v39, 4, v0
	v_ashrrev_i32_e32 v23, 31, v22
	v_ashrrev_i32_e32 v25, 31, v24
	v_and_b32_e32 v0, 0xffffff00, v1
	v_and_b32_e32 v35, -4, v34
	v_lshlrev_b64 v[26:27], 13, v[22:23]
	v_lshlrev_b64 v[28:29], 13, v[24:25]
	v_lshl_add_u32 v23, v22, 2, v2
	v_lshl_add_u32 v25, v24, 2, v2
	v_lshl_add_u32 v40, v38, 2, v2
	v_lshl_add_u32 v41, v39, 2, v2
	v_add3_u32 v42, v2, v3, v0
	v_or_b32_e32 v1, 3, v34
	v_lshlrev_b32_e32 v2, 2, v34
	v_lshl_add_u32 v36, v21, 2, 0
	v_mul_lo_u32 v0, v35, s2
	v_mul_lo_u32 v1, v1, s2
	v_and_b32_e32 v2, -16, v2
	v_readlane_b32 s2, v255, 8
	s_addk_i32 s4, 0xff80
	v_add_u32_e32 v44, v36, v0
	v_add_u32_e32 v43, s2, v2
	v_add_u32_e32 v45, v36, v1
	s_branch .LBB0_505
.LBB0_504:
	s_add_i32 s2, s4, 0x80
	s_cmpk_lt_i32 s4, 0x380
	s_mov_b32 s4, s2
	s_waitcnt lgkmcnt(0)
	global_store_dwordx4 v[30:31], v[12:15], off offset:48
	s_cbranch_scc0 .LBB0_511

.LBB0_615:
	s_or_b64 exec, exec, s[48:49]
	s_mov_b64 s[2:3], s[96:97]
	s_mov_b32 s5, s93
	s_mov_b32 s4, s94
	s_add_i32 s6, s5, 0x400
	s_cmpk_eq_i32 s4, 0x100
	s_cselect_b32 s5, s6, s5
	v_mov_b32_e32 v0, v192
	s_cmpk_lt_i32 s5, 0x800
	s_movk_i32 s8, 0x800
	s_cbranch_scc0 .LBB0_625
	s_load_dwordx2 s[6:7], s[2:3], 0x50
	s_load_dwordx4 s[40:43], s[2:3], 0xc0
	v_readlane_b32 s8, v255, 20
	v_readlane_b32 s9, v255, 21
	s_mov_b32 s9, s75
	s_lshl_b64 s[2:3], s[8:9], 21
	s_mov_b32 s10, s8
	s_lshl_b64 s[8:9], s[8:9], 19
	s_waitcnt lgkmcnt(0)
	s_add_u32 s6, s6, s8
	s_addc_u32 s7, s7, s9
	v_lshlrev_b32_e32 v1, 2, v0
	s_add_u32 s2, s42, s2
	v_and_b32_e32 v4, 60, v1
	s_addc_u32 s3, s43, s3
	v_lshlrev_b32_e32 v194, 2, v4
	v_lshl_add_u64 v[2:3], s[2:3], 0, v[194:195]
	s_mov_b64 s[2:3], 0x22200000
	v_and_b32_e32 v21, 0x7c, v1
	v_lshlrev_b32_e32 v1, 4, v0
	v_lshl_add_u64 v[16:17], v[2:3], 0, s[2:3]
	s_movk_i32 s2, 0x210
	v_ashrrev_i32_e32 v34, 3, v0
	v_and_b32_e32 v20, 0x70, v1
	v_mad_u32_u24 v2, v4, s2, 0
	v_mul_i32_i24_e32 v3, 0xfffffdf4, v4
	v_mul_lo_u32 v4, v34, s2
	v_lshlrev_b32_e32 v5, 2, v20
	v_add3_u32 v37, 0, v4, v5
	v_add_u32_e32 v4, 0x200, v0
	v_ashrrev_i32_e32 v22, 4, v0
	v_ashrrev_i32_e32 v24, 4, v4
	v_add_u32_e32 v4, 0x400, v0
	v_add_u32_e32 v0, 0x600, v0
	v_writelane_b32 v255, s10, 20
	v_ashrrev_i32_e32 v38, 4, v4
	v_ashrrev_i32_e32 v39, 4, v0
	v_ashrrev_i32_e32 v23, 31, v22
	v_ashrrev_i32_e32 v25, 31, v24
	v_and_b32_e32 v0, 0xffffff00, v1
	v_writelane_b32 v255, s11, 21
	v_and_b32_e32 v35, -4, v34
	v_lshlrev_b64 v[26:27], 13, v[22:23]
	v_lshlrev_b64 v[28:29], 13, v[24:25]
	v_lshl_add_u32 v23, v22, 2, v2
	v_lshl_add_u32 v25, v24, 2, v2
	v_lshl_add_u32 v40, v38, 2, v2
	v_lshl_add_u32 v41, v39, 2, v2
	v_add3_u32 v42, v2, v3, v0
	v_or_b32_e32 v1, 3, v34
	v_lshlrev_b32_e32 v2, 2, v34
	v_lshl_add_u32 v36, v21, 2, 0
	v_mul_lo_u32 v0, v35, s2
	v_mul_lo_u32 v1, v1, s2
	v_and_b32_e32 v2, -16, v2
	v_readlane_b32 s2, v255, 8
	v_lshl_add_u64 v[18:19], s[6:7], 0, v[194:195]
	v_add_u32_e32 v44, v36, v0
	v_add_u32_e32 v43, s2, v2
	v_add_u32_e32 v45, v36, v1
	s_branch .LBB0_618
